# grid barrier: L1 invalidate issued at arrival (before polling / right behind wbl2) instead of after the release; on top of barcache+strip+sbtrim
# baseline (speedup 1.0000x reference)
; __device__ __forceinline__ unsigned xb_ld(unsigned* p)              { return __hip_atomic_load(p, __ATOMIC_RELAXED, __HIP_MEMORY_SCOPE_AGENT); }
; __device__ __forceinline__ unsigned xb_add(unsigned* p, unsigned v) { return __hip_atomic_fetch_add(p, v, __ATOMIC_RELAXED, __HIP_MEMORY_SCOPE_AGENT); }
; #define XB_SPIN(cond, bar) do { unsigned _sp = 0; while (cond) { __builtin_amdgcn_s_sleep(1); \
;     if ((++_sp & 255u) == 0u) { if (xb_ld(&(bar)[XB_TMO])) break; if (_sp > XB_SPIN_CAP) { atomicAdd(&(bar)[XB_TMO], 1u); break; } } } } while (0)
; __device__ __forceinline__ void xcd_barrier(const XcdBarrier& b) {
;     ...
;         unsigned nloc = b.st[0], nx = b.st[1];
;         if (nloc == 0u) { xcd_barrier_complete(bar, b.x, nloc, nx); b.st[0] = nloc; b.st[1] = nx; }
;         const unsigned old = xb_add(&bar[XB_XSUB(b.x)], 1u);
;         const unsigned gen = old / nloc;
;         if (old + 1u == (gen + 1u) * nloc) {
;             __builtin_amdgcn_fence(__ATOMIC_RELEASE, "agent");
;             asm volatile("s_waitcnt vmcnt(0)" ::: "memory");
;             const unsigned og = xb_add(&bar[XB_TOP], 1u);
;             const unsigned tg = og / nx;
;             if (og + 1u == (tg + 1u) * nx) xb_add(&bar[XB_TOPGEN], 1u);
;             else XB_SPIN(xb_ld(&bar[XB_TOPGEN]) == tg, bar);
;             __builtin_amdgcn_fence(__ATOMIC_ACQUIRE, "agent");
;             xb_add(&bar[XB_XGEN(b.x)], 1u);
;             asm volatile("s_waitcnt vmcnt(0)" ::: "memory");
;         } else {
;             XB_SPIN(xb_ld(&bar[XB_XGEN(b.x)]) == gen, bar);
.LBB0_66:
	s_or_b64 exec, exec, s[4:5]
	v_mov_b32_e32 v1, 0x25100
	ds_write_b32 v1, v2
	ds_write_b32 v1, v0 offset:4
	s_lshl_b32 s4, s25, 8
	s_add_u32 s4, s66, s4
	s_addc_u32 s5, s67, 0
	v_mov_b32_e32 v1, 0x1000
	v_mov_b32_e32 v3, 1
	global_atomic_add v1, v1, v3, s[4:5] offset:1024 sc0
	v_cvt_f32_u32_e32 v3, v2
	v_sub_u32_e32 v4, 0, v2
	v_rcp_iflag_f32_e32 v3, v3
	s_nop 0
	v_mul_f32_e32 v3, 0x4f7ffffe, v3
	v_cvt_u32_f32_e32 v3, v3
	v_mul_lo_u32 v4, v4, v3
	v_mul_hi_u32 v4, v3, v4
	v_add_u32_e32 v3, v3, v4
	s_waitcnt vmcnt(0)
	v_mul_hi_u32 v3, v1, v3
	v_mul_lo_u32 v5, v3, v2
	v_add_u32_e32 v4, 1, v1
	v_sub_u32_e32 v1, v1, v5
	v_add_u32_e32 v6, 1, v3
	v_cmp_ge_u32_e32 vcc, v1, v2
	v_sub_u32_e32 v5, v1, v2
	s_nop 0
	v_cndmask_b32_e32 v3, v3, v6, vcc
	v_cndmask_b32_e32 v1, v1, v5, vcc
	v_add_u32_e32 v5, 1, v3
	v_cmp_ge_u32_e32 vcc, v1, v2
	s_nop 1
	v_cndmask_b32_e32 v1, v3, v5, vcc
	v_mad_u64_u32 v[2:3], s[6:7], v2, v1, v[2:3]
	v_cmp_ne_u32_e32 vcc, v4, v2
	s_and_saveexec_b64 s[6:7], vcc
	s_xor_b64 s[6:7], exec, s[6:7]
	s_cbranch_execz .LBB0_80
	buffer_inv sc1
	v_mov_b32_e32 v0, 0x2000
	global_load_dword v0, v0, s[4:5] offset:1024 sc1
	s_add_u32 s10, s4, 0x2400
	s_addc_u32 s11, s5, 0
	s_waitcnt vmcnt(0)
	v_cmp_eq_u32_e32 vcc, v0, v1
	s_and_saveexec_b64 s[8:9], vcc
	s_cbranch_execz .LBB0_79
	s_mov_b32 s22, 1
	s_mov_b64 s[12:13], 0
	v_mov_b32_e32 v0, 0
	s_branch .LBB0_70

; __device__ __forceinline__ unsigned xb_ld(unsigned* p)              { return __hip_atomic_load(p, __ATOMIC_RELAXED, __HIP_MEMORY_SCOPE_AGENT); }
; __device__ __forceinline__ unsigned xb_add(unsigned* p, unsigned v) { return __hip_atomic_fetch_add(p, v, __ATOMIC_RELAXED, __HIP_MEMORY_SCOPE_AGENT); }
; #define XB_SPIN(cond, bar) do { unsigned _sp = 0; while (cond) { __builtin_amdgcn_s_sleep(1); \
;     if ((++_sp & 255u) == 0u) { if (xb_ld(&(bar)[XB_TMO])) break; if (_sp > XB_SPIN_CAP) { atomicAdd(&(bar)[XB_TMO], 1u); break; } } } } while (0)
; __device__ __forceinline__ void xcd_barrier(const XcdBarrier& b) {
;     ...
;         if (old + 1u == (gen + 1u) * nloc) {
;             __builtin_amdgcn_fence(__ATOMIC_RELEASE, "agent");
;             asm volatile("s_waitcnt vmcnt(0)" ::: "memory");
;             const unsigned og = xb_add(&bar[XB_TOP], 1u);
;             const unsigned tg = og / nx;
;             if (og + 1u == (tg + 1u) * nx) xb_add(&bar[XB_TOPGEN], 1u);
;             else XB_SPIN(xb_ld(&bar[XB_TOPGEN]) == tg, bar);
;             __builtin_amdgcn_fence(__ATOMIC_ACQUIRE, "agent");
;             xb_add(&bar[XB_XGEN(b.x)], 1u);
;             asm volatile("s_waitcnt vmcnt(0)" ::: "memory");
;         } else {
;             XB_SPIN(xb_ld(&bar[XB_XGEN(b.x)]) == gen, bar);
;             __builtin_amdgcn_fence(__ATOMIC_ACQUIRE, "agent");
.LBB0_79:
	s_or_b64 exec, exec, s[8:9]
	s_waitcnt vmcnt(0) lgkmcnt(0)
	s_waitcnt vmcnt(0)
.LBB0_80:
	s_andn2_saveexec_b64 s[6:7], s[6:7]
	s_cbranch_execz .LBB0_98
	s_mov_b64 s[6:7], exec
	buffer_wbl2 sc1
	buffer_inv sc1
	s_waitcnt lgkmcnt(0)
	s_waitcnt vmcnt(0)
	v_mbcnt_lo_u32_b32 v1, s6, 0
	v_mbcnt_hi_u32_b32 v1, s7, v1
	v_cmp_eq_u32_e32 vcc, 0, v1
	s_and_saveexec_b64 s[8:9], vcc
	s_cbranch_execz .LBB0_83
	s_bcnt1_i32_b64 s6, s[6:7]
	v_mov_b32_e32 v2, 0x3000
	v_mov_b32_e32 v3, s6
	global_atomic_add v2, v2, v3, s[66:67] offset:1024 sc0

; __device__ __forceinline__ unsigned xb_ld(unsigned* p)              { return __hip_atomic_load(p, __ATOMIC_RELAXED, __HIP_MEMORY_SCOPE_AGENT); }
; __device__ __forceinline__ unsigned xb_add(unsigned* p, unsigned v) { return __hip_atomic_fetch_add(p, v, __ATOMIC_RELAXED, __HIP_MEMORY_SCOPE_AGENT); }
; #define XB_SPIN(cond, bar) do { unsigned _sp = 0; while (cond) { __builtin_amdgcn_s_sleep(1); \
;     if ((++_sp & 255u) == 0u) { if (xb_ld(&(bar)[XB_TMO])) break; if (_sp > XB_SPIN_CAP) { atomicAdd(&(bar)[XB_TMO], 1u); break; } } } } while (0)
; __device__ __forceinline__ void xcd_barrier(const XcdBarrier& b) {
;     ...
;             if (og + 1u == (tg + 1u) * nx) xb_add(&bar[XB_TOPGEN], 1u);
;             else XB_SPIN(xb_ld(&bar[XB_TOPGEN]) == tg, bar);
;             __builtin_amdgcn_fence(__ATOMIC_ACQUIRE, "agent");
;             xb_add(&bar[XB_XGEN(b.x)], 1u);
.LBB0_97:
	s_or_b64 exec, exec, s[6:7]
	v_mov_b32_e32 v0, 0x2000
	v_mov_b32_e32 v1, 1
	s_waitcnt vmcnt(0)
	s_nop 0
	global_atomic_add v0, v1, s[4:5] offset:1024
	s_waitcnt vmcnt(0)

; __device__ __forceinline__ unsigned xb_add(unsigned* p, unsigned v) { return __hip_atomic_fetch_add(p, v, __ATOMIC_RELAXED, __HIP_MEMORY_SCOPE_AGENT); }
; __device__ __forceinline__ void xcd_barrier(const XcdBarrier& b) {
;     ...
;             __builtin_amdgcn_fence(__ATOMIC_ACQUIRE, "agent");
;             xb_add(&bar[XB_XGEN(b.x)], 1u);
.LBB0_100:
	s_or_b64 exec, exec, s[8:9]
	v_readlane_b32 s4, v254, 10
	v_readlane_b32 s5, v254, 11
	s_waitcnt vmcnt(0)
	s_nop 0
	s_nop 2
	global_atomic_add v0, v252, s[4:5]
	s_waitcnt vmcnt(0)

; __device__ __forceinline__ unsigned xb_ld(unsigned* p)              { return __hip_atomic_load(p, __ATOMIC_RELAXED, __HIP_MEMORY_SCOPE_AGENT); }
; __device__ __forceinline__ unsigned xb_add(unsigned* p, unsigned v) { return __hip_atomic_fetch_add(p, v, __ATOMIC_RELAXED, __HIP_MEMORY_SCOPE_AGENT); }
; #define XB_SPIN(cond, bar) do { unsigned _sp = 0; while (cond) { __builtin_amdgcn_s_sleep(1); \
;     if ((++_sp & 255u) == 0u) { if (xb_ld(&(bar)[XB_TMO])) break; if (_sp > XB_SPIN_CAP) { atomicAdd(&(bar)[XB_TMO], 1u); break; } } } } while (0)
; __device__ __forceinline__ void xcd_barrier(const XcdBarrier& b) {
;     ...
;         const unsigned old = xb_add(&bar[XB_XSUB(b.x)], 1u);
;         const unsigned gen = old / nloc;
;         if (old + 1u == (gen + 1u) * nloc) {
;             __builtin_amdgcn_fence(__ATOMIC_RELEASE, "agent");
;             asm volatile("s_waitcnt vmcnt(0)" ::: "memory");
;             const unsigned og = xb_add(&bar[XB_TOP], 1u);
;             const unsigned tg = og / nx;
;             if (og + 1u == (tg + 1u) * nx) xb_add(&bar[XB_TOPGEN], 1u);
;             else XB_SPIN(xb_ld(&bar[XB_TOPGEN]) == tg, bar);
;             __builtin_amdgcn_fence(__ATOMIC_ACQUIRE, "agent");
;             xb_add(&bar[XB_XGEN(b.x)], 1u);
;             asm volatile("s_waitcnt vmcnt(0)" ::: "memory");
;         } else {
;             XB_SPIN(xb_ld(&bar[XB_XGEN(b.x)]) == gen, bar);
.LBB0_357:
	s_or_b64 exec, exec, s[8:9]
	v_readlane_b32 s8, v254, 8
	v_readlane_b32 s9, v254, 9
	v_cvt_f32_u32_e32 v1, v4
	v_sub_u32_e32 v5, 0, v4
	v_rcp_iflag_f32_e32 v1, v1
	s_nop 1
	global_atomic_add v3, v0, v252, s[8:9] sc0
	v_mul_f32_e32 v1, 0x4f7ffffe, v1
	v_cvt_u32_f32_e32 v1, v1
	v_mul_lo_u32 v5, v5, v1
	v_mul_hi_u32 v5, v1, v5
	v_add_u32_e32 v1, v1, v5
	s_waitcnt vmcnt(0)
	v_mul_hi_u32 v1, v3, v1
	v_mul_lo_u32 v5, v1, v4
	v_sub_u32_e32 v5, v3, v5
	v_cmp_ge_u32_e32 vcc, v5, v4
	v_add_u32_e32 v6, 1, v1
	v_add_u32_e32 v3, 1, v3
	v_cndmask_b32_e32 v1, v1, v6, vcc
	v_sub_u32_e32 v6, v5, v4
	v_cndmask_b32_e32 v5, v5, v6, vcc
	v_cmp_ge_u32_e32 vcc, v5, v4
	v_add_u32_e32 v5, 1, v1
	s_nop 0
	v_cndmask_b32_e32 v1, v1, v5, vcc
	v_mad_u64_u32 v[4:5], s[8:9], v4, v1, v[4:5]
	v_cmp_ne_u32_e32 vcc, v3, v4
	s_and_saveexec_b64 s[8:9], vcc
	s_xor_b64 s[8:9], exec, s[8:9]
	s_cbranch_execz .LBB0_371
	buffer_inv sc1
	v_readlane_b32 s10, v254, 10
	v_readlane_b32 s11, v254, 11
	s_nop 4
	global_load_dword v2, v0, s[10:11] sc1
	s_waitcnt vmcnt(0)
	v_cmp_eq_u32_e32 vcc, v2, v1
	s_and_saveexec_b64 s[14:15], vcc
	s_cbranch_execz .LBB0_370
	s_mov_b32 s5, 1
	s_mov_b64 s[16:17], 0
	s_branch .LBB0_361

; __device__ __forceinline__ unsigned xb_ld(unsigned* p)              { return __hip_atomic_load(p, __ATOMIC_RELAXED, __HIP_MEMORY_SCOPE_AGENT); }
; __device__ __forceinline__ unsigned xb_add(unsigned* p, unsigned v) { return __hip_atomic_fetch_add(p, v, __ATOMIC_RELAXED, __HIP_MEMORY_SCOPE_AGENT); }
; #define XB_SPIN(cond, bar) do { unsigned _sp = 0; while (cond) { __builtin_amdgcn_s_sleep(1); \
;     if ((++_sp & 255u) == 0u) { if (xb_ld(&(bar)[XB_TMO])) break; if (_sp > XB_SPIN_CAP) { atomicAdd(&(bar)[XB_TMO], 1u); break; } } } } while (0)
; __device__ __forceinline__ void xcd_barrier(const XcdBarrier& b) {
;     ...
;         if (old + 1u == (gen + 1u) * nloc) {
;             __builtin_amdgcn_fence(__ATOMIC_RELEASE, "agent");
;             asm volatile("s_waitcnt vmcnt(0)" ::: "memory");
;             const unsigned og = xb_add(&bar[XB_TOP], 1u);
;             const unsigned tg = og / nx;
;             if (og + 1u == (tg + 1u) * nx) xb_add(&bar[XB_TOPGEN], 1u);
;             else XB_SPIN(xb_ld(&bar[XB_TOPGEN]) == tg, bar);
;             __builtin_amdgcn_fence(__ATOMIC_ACQUIRE, "agent");
;             xb_add(&bar[XB_XGEN(b.x)], 1u);
;             asm volatile("s_waitcnt vmcnt(0)" ::: "memory");
;         } else {
;             XB_SPIN(xb_ld(&bar[XB_XGEN(b.x)]) == gen, bar);
;             __builtin_amdgcn_fence(__ATOMIC_ACQUIRE, "agent");
.LBB0_370:
	s_or_b64 exec, exec, s[14:15]
	s_waitcnt vmcnt(0) lgkmcnt(0)
	s_waitcnt vmcnt(0)
.LBB0_371:
	s_andn2_saveexec_b64 s[8:9], s[8:9]
	s_cbranch_execz .LBB0_389
	s_mov_b64 s[8:9], exec
	buffer_wbl2 sc1
	buffer_inv sc1
	s_waitcnt lgkmcnt(0)
	s_waitcnt vmcnt(0)
	v_mbcnt_lo_u32_b32 v1, s8, 0
	v_mbcnt_hi_u32_b32 v1, s9, v1
	v_cmp_eq_u32_e32 vcc, 0, v1
	s_and_saveexec_b64 s[14:15], vcc
	s_cbranch_execz .LBB0_374
	s_bcnt1_i32_b64 s5, s[8:9]
	v_readlane_b32 s8, v254, 12
	v_mov_b32_e32 v3, s5
	v_readlane_b32 s9, v254, 13
	s_nop 4
	global_atomic_add v3, v0, v3, s[8:9] sc0

; __device__ __forceinline__ unsigned xb_add(unsigned* p, unsigned v) { return __hip_atomic_fetch_add(p, v, __ATOMIC_RELAXED, __HIP_MEMORY_SCOPE_AGENT); }
; __device__ __forceinline__ void xcd_barrier(const XcdBarrier& b) {
;     ...
;             __builtin_amdgcn_fence(__ATOMIC_ACQUIRE, "agent");
;             xb_add(&bar[XB_XGEN(b.x)], 1u);
.LBB0_388:
	s_or_b64 exec, exec, s[8:9]
	v_readlane_b32 s8, v254, 10
	v_readlane_b32 s9, v254, 11
	s_waitcnt vmcnt(0)
	s_nop 0
	s_nop 2
	global_atomic_add v0, v252, s[8:9]
	s_waitcnt vmcnt(0)

; __device__ __forceinline__ unsigned xb_ld(unsigned* p)              { return __hip_atomic_load(p, __ATOMIC_RELAXED, __HIP_MEMORY_SCOPE_AGENT); }
; __device__ __forceinline__ unsigned xb_add(unsigned* p, unsigned v) { return __hip_atomic_fetch_add(p, v, __ATOMIC_RELAXED, __HIP_MEMORY_SCOPE_AGENT); }
; #define XB_SPIN(cond, bar) do { unsigned _sp = 0; while (cond) { __builtin_amdgcn_s_sleep(1); \
;     if ((++_sp & 255u) == 0u) { if (xb_ld(&(bar)[XB_TMO])) break; if (_sp > XB_SPIN_CAP) { atomicAdd(&(bar)[XB_TMO], 1u); break; } } } } while (0)
; __device__ __forceinline__ void xcd_barrier(const XcdBarrier& b) {
;     ...
;         const unsigned old = xb_add(&bar[XB_XSUB(b.x)], 1u);
;         const unsigned gen = old / nloc;
;         if (old + 1u == (gen + 1u) * nloc) {
;             __builtin_amdgcn_fence(__ATOMIC_RELEASE, "agent");
;             asm volatile("s_waitcnt vmcnt(0)" ::: "memory");
;             const unsigned og = xb_add(&bar[XB_TOP], 1u);
;             const unsigned tg = og / nx;
;             if (og + 1u == (tg + 1u) * nx) xb_add(&bar[XB_TOPGEN], 1u);
;             else XB_SPIN(xb_ld(&bar[XB_TOPGEN]) == tg, bar);
;             __builtin_amdgcn_fence(__ATOMIC_ACQUIRE, "agent");
;             xb_add(&bar[XB_XGEN(b.x)], 1u);
;             asm volatile("s_waitcnt vmcnt(0)" ::: "memory");
;         } else {
;             XB_SPIN(xb_ld(&bar[XB_XGEN(b.x)]) == gen, bar);
.LBB0_1176:
	s_or_b64 exec, exec, s[8:9]
	v_readlane_b32 s4, v254, 8
	v_readlane_b32 s5, v254, 9
	v_cvt_f32_u32_e32 v1, v4
	v_sub_u32_e32 v5, 0, v4
	v_rcp_iflag_f32_e32 v1, v1
	s_nop 1
	global_atomic_add v3, v0, v252, s[4:5] sc0
	v_mul_f32_e32 v1, 0x4f7ffffe, v1
	v_cvt_u32_f32_e32 v1, v1
	v_mul_lo_u32 v5, v5, v1
	v_mul_hi_u32 v5, v1, v5
	v_add_u32_e32 v1, v1, v5
	s_waitcnt vmcnt(0)
	v_mul_hi_u32 v1, v3, v1
	v_mul_lo_u32 v5, v1, v4
	v_sub_u32_e32 v5, v3, v5
	v_cmp_ge_u32_e32 vcc, v5, v4
	v_add_u32_e32 v6, 1, v1
	v_add_u32_e32 v3, 1, v3
	v_cndmask_b32_e32 v1, v1, v6, vcc
	v_sub_u32_e32 v6, v5, v4
	v_cndmask_b32_e32 v5, v5, v6, vcc
	v_cmp_ge_u32_e32 vcc, v5, v4
	v_add_u32_e32 v5, 1, v1
	s_nop 0
	v_cndmask_b32_e32 v1, v1, v5, vcc
	v_mad_u64_u32 v[4:5], s[4:5], v4, v1, v[4:5]
	v_cmp_ne_u32_e32 vcc, v3, v4
	s_and_saveexec_b64 s[4:5], vcc
	s_xor_b64 s[8:9], exec, s[4:5]
	s_cbranch_execz .LBB0_1190
	buffer_inv sc1
	v_readlane_b32 s4, v254, 10
	v_readlane_b32 s5, v254, 11
	s_nop 4
	global_load_dword v2, v0, s[4:5] sc1
	s_waitcnt vmcnt(0)
	v_cmp_eq_u32_e32 vcc, v2, v1
	s_and_saveexec_b64 s[10:11], vcc
	s_cbranch_execz .LBB0_1189
	s_mov_b32 s4, 1
	s_mov_b64 s[14:15], 0
	s_branch .LBB0_1180

; __device__ __forceinline__ unsigned xb_ld(unsigned* p)              { return __hip_atomic_load(p, __ATOMIC_RELAXED, __HIP_MEMORY_SCOPE_AGENT); }
; __device__ __forceinline__ unsigned xb_add(unsigned* p, unsigned v) { return __hip_atomic_fetch_add(p, v, __ATOMIC_RELAXED, __HIP_MEMORY_SCOPE_AGENT); }
; #define XB_SPIN(cond, bar) do { unsigned _sp = 0; while (cond) { __builtin_amdgcn_s_sleep(1); \
;     if ((++_sp & 255u) == 0u) { if (xb_ld(&(bar)[XB_TMO])) break; if (_sp > XB_SPIN_CAP) { atomicAdd(&(bar)[XB_TMO], 1u); break; } } } } while (0)
; __device__ __forceinline__ void xcd_barrier(const XcdBarrier& b) {
;     ...
;         if (old + 1u == (gen + 1u) * nloc) {
;             __builtin_amdgcn_fence(__ATOMIC_RELEASE, "agent");
;             asm volatile("s_waitcnt vmcnt(0)" ::: "memory");
;             const unsigned og = xb_add(&bar[XB_TOP], 1u);
;             const unsigned tg = og / nx;
;             if (og + 1u == (tg + 1u) * nx) xb_add(&bar[XB_TOPGEN], 1u);
;             else XB_SPIN(xb_ld(&bar[XB_TOPGEN]) == tg, bar);
;             __builtin_amdgcn_fence(__ATOMIC_ACQUIRE, "agent");
;             xb_add(&bar[XB_XGEN(b.x)], 1u);
;             asm volatile("s_waitcnt vmcnt(0)" ::: "memory");
;         } else {
;             XB_SPIN(xb_ld(&bar[XB_XGEN(b.x)]) == gen, bar);
;             __builtin_amdgcn_fence(__ATOMIC_ACQUIRE, "agent");
.LBB0_1189:
	s_or_b64 exec, exec, s[10:11]
	s_waitcnt vmcnt(0) lgkmcnt(0)
	s_waitcnt vmcnt(0)
.LBB0_1190:
	s_andn2_saveexec_b64 s[4:5], s[8:9]
	s_cbranch_execz .LBB0_101
	s_mov_b64 s[8:9], exec
	buffer_wbl2 sc1
	buffer_inv sc1
	s_waitcnt lgkmcnt(0)
	s_waitcnt vmcnt(0)
	v_mbcnt_lo_u32_b32 v1, s8, 0
	v_mbcnt_hi_u32_b32 v1, s9, v1
	v_cmp_eq_u32_e32 vcc, 0, v1
	s_and_saveexec_b64 s[10:11], vcc
	s_cbranch_execz .LBB0_1193
	s_bcnt1_i32_b64 s4, s[8:9]
	v_mov_b32_e32 v3, s4
	v_readlane_b32 s4, v254, 12
	v_readlane_b32 s5, v254, 13
	s_nop 4
	global_atomic_add v3, v0, v3, s[4:5] sc0

; __device__ __forceinline__ unsigned xb_ld(unsigned* p)              { return __hip_atomic_load(p, __ATOMIC_RELAXED, __HIP_MEMORY_SCOPE_AGENT); }
; __device__ __forceinline__ unsigned xb_add(unsigned* p, unsigned v) { return __hip_atomic_fetch_add(p, v, __ATOMIC_RELAXED, __HIP_MEMORY_SCOPE_AGENT); }
; #define XB_SPIN(cond, bar) do { unsigned _sp = 0; while (cond) { __builtin_amdgcn_s_sleep(1); \
;     if ((++_sp & 255u) == 0u) { if (xb_ld(&(bar)[XB_TMO])) break; if (_sp > XB_SPIN_CAP) { atomicAdd(&(bar)[XB_TMO], 1u); break; } } } } while (0)
; __device__ __forceinline__ void xcd_barrier(const XcdBarrier& b) {
;     ...
;         const unsigned old = xb_add(&bar[XB_XSUB(b.x)], 1u);
;         const unsigned gen = old / nloc;
;         if (old + 1u == (gen + 1u) * nloc) {
;             __builtin_amdgcn_fence(__ATOMIC_RELEASE, "agent");
;             asm volatile("s_waitcnt vmcnt(0)" ::: "memory");
;             const unsigned og = xb_add(&bar[XB_TOP], 1u);
;             const unsigned tg = og / nx;
;             if (og + 1u == (tg + 1u) * nx) xb_add(&bar[XB_TOPGEN], 1u);
;             else XB_SPIN(xb_ld(&bar[XB_TOPGEN]) == tg, bar);
;             __builtin_amdgcn_fence(__ATOMIC_ACQUIRE, "agent");
;             xb_add(&bar[XB_XGEN(b.x)], 1u);
;             asm volatile("s_waitcnt vmcnt(0)" ::: "memory");
;         } else {
;             XB_SPIN(xb_ld(&bar[XB_XGEN(b.x)]) == gen, bar);
.LBB0_1225:
	s_or_b64 exec, exec, s[4:5]
	v_readlane_b32 s4, v254, 8
	v_mov_b32_e32 v3, 0
	v_mov_b32_e32 v1, 1
	v_readlane_b32 s5, v254, 9
	v_cvt_f32_u32_e32 v4, v2
	v_sub_u32_e32 v5, 0, v2
	v_rcp_iflag_f32_e32 v4, v4
	s_nop 1
	global_atomic_add v1, v3, v1, s[4:5] sc0
	v_mul_f32_e32 v4, 0x4f7ffffe, v4
	v_cvt_u32_f32_e32 v4, v4
	v_mul_lo_u32 v5, v5, v4
	v_mul_hi_u32 v5, v4, v5
	v_add_u32_e32 v4, v4, v5
	s_waitcnt vmcnt(0)
	v_mul_hi_u32 v4, v1, v4
	v_mul_lo_u32 v5, v4, v2
	v_add_u32_e32 v6, 1, v1
	v_sub_u32_e32 v1, v1, v5
	v_add_u32_e32 v7, 1, v4
	v_cmp_ge_u32_e32 vcc, v1, v2
	v_sub_u32_e32 v5, v1, v2
	s_nop 0
	v_cndmask_b32_e32 v4, v4, v7, vcc
	v_cndmask_b32_e32 v1, v1, v5, vcc
	v_add_u32_e32 v5, 1, v4
	v_cmp_ge_u32_e32 vcc, v1, v2
	s_nop 1
	v_cndmask_b32_e32 v1, v4, v5, vcc
	v_mad_u64_u32 v[4:5], s[4:5], v2, v1, v[2:3]
	v_cmp_ne_u32_e32 vcc, v6, v4
	s_and_saveexec_b64 s[4:5], vcc
	s_xor_b64 s[4:5], exec, s[4:5]
	s_cbranch_execz .LBB0_1239
	buffer_inv sc1
	v_readlane_b32 s6, v254, 10
	v_readlane_b32 s7, v254, 11
	s_nop 4
	global_load_dword v0, v3, s[6:7] sc1
	s_waitcnt vmcnt(0)
	v_cmp_eq_u32_e32 vcc, v0, v1
	s_and_saveexec_b64 s[6:7], vcc
	s_cbranch_execz .LBB0_1238
	s_mov_b32 s3, 1
	s_mov_b64 s[8:9], 0
	v_mov_b32_e32 v0, 0
	s_branch .LBB0_1229

; __device__ __forceinline__ unsigned xb_ld(unsigned* p)              { return __hip_atomic_load(p, __ATOMIC_RELAXED, __HIP_MEMORY_SCOPE_AGENT); }
; __device__ __forceinline__ unsigned xb_add(unsigned* p, unsigned v) { return __hip_atomic_fetch_add(p, v, __ATOMIC_RELAXED, __HIP_MEMORY_SCOPE_AGENT); }
; #define XB_SPIN(cond, bar) do { unsigned _sp = 0; while (cond) { __builtin_amdgcn_s_sleep(1); \
;     if ((++_sp & 255u) == 0u) { if (xb_ld(&(bar)[XB_TMO])) break; if (_sp > XB_SPIN_CAP) { atomicAdd(&(bar)[XB_TMO], 1u); break; } } } } while (0)
; __device__ __forceinline__ void xcd_barrier(const XcdBarrier& b) {
;     ...
;         if (old + 1u == (gen + 1u) * nloc) {
;             __builtin_amdgcn_fence(__ATOMIC_RELEASE, "agent");
;             asm volatile("s_waitcnt vmcnt(0)" ::: "memory");
;             const unsigned og = xb_add(&bar[XB_TOP], 1u);
;             const unsigned tg = og / nx;
;             if (og + 1u == (tg + 1u) * nx) xb_add(&bar[XB_TOPGEN], 1u);
;             else XB_SPIN(xb_ld(&bar[XB_TOPGEN]) == tg, bar);
;             __builtin_amdgcn_fence(__ATOMIC_ACQUIRE, "agent");
;             xb_add(&bar[XB_XGEN(b.x)], 1u);
;             asm volatile("s_waitcnt vmcnt(0)" ::: "memory");
;         } else {
;             XB_SPIN(xb_ld(&bar[XB_XGEN(b.x)]) == gen, bar);
;             __builtin_amdgcn_fence(__ATOMIC_ACQUIRE, "agent");
.LBB0_1238:
	s_or_b64 exec, exec, s[6:7]
	s_waitcnt vmcnt(0) lgkmcnt(0)
	s_waitcnt vmcnt(0)
.LBB0_1239:
	s_andn2_saveexec_b64 s[4:5], s[4:5]
	s_cbranch_execz .LBB0_1257
	s_mov_b64 s[4:5], exec
	buffer_wbl2 sc1
	buffer_inv sc1
	s_waitcnt lgkmcnt(0)
	s_waitcnt vmcnt(0)
	v_mbcnt_lo_u32_b32 v1, s4, 0
	v_mbcnt_hi_u32_b32 v1, s5, v1
	v_cmp_eq_u32_e32 vcc, 0, v1
	s_and_saveexec_b64 s[6:7], vcc
	s_cbranch_execz .LBB0_1242
	s_bcnt1_i32_b64 s3, s[4:5]
	v_readlane_b32 s4, v254, 12
	v_mov_b32_e32 v2, 0
	v_mov_b32_e32 v3, s3
	v_readlane_b32 s5, v254, 13
	s_nop 4
	global_atomic_add v2, v2, v3, s[4:5] sc0

; __device__ __forceinline__ unsigned xb_add(unsigned* p, unsigned v) { return __hip_atomic_fetch_add(p, v, __ATOMIC_RELAXED, __HIP_MEMORY_SCOPE_AGENT); }
; __device__ __forceinline__ void xcd_barrier(const XcdBarrier& b) {
;     ...
;             __builtin_amdgcn_fence(__ATOMIC_ACQUIRE, "agent");
;             xb_add(&bar[XB_XGEN(b.x)], 1u);
;             asm volatile("s_waitcnt vmcnt(0)" ::: "memory");
.LBB0_1256:
	s_or_b64 exec, exec, s[4:5]
	v_readlane_b32 s4, v254, 10
	v_mov_b32_e32 v0, 0
	v_mov_b32_e32 v1, 1
	v_readlane_b32 s5, v254, 11
	s_waitcnt vmcnt(0)
	s_nop 0
	s_nop 2
	global_atomic_add v0, v1, s[4:5]
	s_waitcnt vmcnt(0)
